# resid GEMM phases (ffn_dn, w_out) also rewritten as 256x128 tiles; epilogue x loads batched 2-deep instead of one-at-a-time
# speedup vs baseline: 1.0557x; 1.0212x over previous
; __device__ __forceinline__ int otid() { int t = threadIdx.x; asm volatile("" : "+v"(t)); return t; }
; __device__ __forceinline__ int frag_off(int fr, int fq) { return (fr >> 3) * 1024 + (fr & 7) * 128 + ((fq ^ ((fr >> 1) & 7)) << 4); }
;   const int tid = otid(), lane = tid & 63, wid = tid >> 6, wr = wid >> 1, wc = wid & 1, fr = lane & 15, fq = lane >> 4;
;   const int o0 = tid * 16;
;   const int lrow = (o0 >> 10) * 8 + ((o0 >> 7) & 7), lcol = ((((o0 >> 4) & 7) ^ ((lrow >> 1) & 7))) * 8;
;   const bf16_t* ag = A + (size_t)lrow * lda + lcol;
;   const bf16_t* bg = Bt + (size_t)lrow * ldb + lcol;
;   const char* A8 = (const char*)A;
;   const char* B8 = (const char*)Bt;
;   unsigned aoff[4], boff[NT];
; #pragma unroll
;   for (int i = 0; i < 4; ++i) aoff[i] = (unsigned)(((lrow + 32 * i) * lda + lcol) * 2);
; #pragma unroll
;   for (int i = 0; i < NT; ++i) boff[i] = (unsigned)(((lrow + (i & 1) * bs1 + (i >> 1) * bs2) * ldb + lcol) * 2);
;   const int wbase = __builtin_amdgcn_readfirstlane(wid) * 1024;
;   const int inner = frag_off(fr, fq);
;   const int abase = wr * 8192 + inner;
;   const int bbase = 16384 + wc * (NT * 2048) + inner;
;   const int nk = K >> 6;
; __device__ __forceinline__ void phase_resid_gemm(const Params& p, const bf16_t* A, int lda, const bf16_t* Wt, int K, int l, int gate_k, float scale,
;                                  bool from_input, int mrows, char* smem, unsigned* tk) {
;   TILE_IDS; (void)tid;
;   for (TileIter ti(mrows / 128, 8, 4, 8, tk); ti.valid();) {
;     int tm, tn; ti.get(tm, tn);
;     ti.prefetch();
;     f32x4 acc[4][4];
;     zero_acc<4>(acc);
;     gemm_main<4>(A + (size_t)tm * 128 * lda, lda, Wt + (size_t)tn * 128 * K, K, K, acc, smem);
;     ti.next(smem);
;     const int bi = mod_idx(tm * 128);
;     const float* gate = mods_ptr(p, l, bi, gate_k);
;     const int row0 = tm * 128 + wr * 64 + fr, col0 = tn * 128 + wc * 64 + fq * 4;
;     const float* xi = xrow_ptr(p, from_input, row0) + col0;
;     float* xo = xrow_out(p, row0) + col0;
;     float4 gv[4];
.LBB0_290:
	s_and_b64 vcc, exec, s[36:37]
	s_cbranch_vccz .LBB0_316
	s_lshr_b32 s23, s22, 7
	s_cmp_eq_u32 s77, 2
	s_cselect_b64 s[34:35], -1, 0
	s_and_b64 s[36:37], s[34:35], exec
	s_cselect_b32 s23, 0x120, s23
	v_mov_b32_e32 v0, v172
	s_cmp_ge_u32 s39, s23
	s_cbranch_scc1 .LBB0_315
	s_and_b64 s[36:37], s[34:35], exec
	s_mov_b32 s36, 0x1600000
	s_cselect_b32 s42, s36, 0x1b80000
	s_xor_b64 s[36:37], s[34:35], -1
	s_cmp_eq_u32 s77, 10
	s_cselect_b64 s[40:41], -1, 0
	v_cndmask_b32_e64 v66, 0.5, 1.0, s[40:41]
	s_and_b64 s[40:41], s[40:41], exec
	s_mov_b32 s40, 0x164a0000
	s_cselect_b32 s98, s40, 0x8b80000
	s_movk_i32 s40, 0xb00
	s_cselect_b32 s60, 0x400, s40
	s_cselect_b32 s43, 5, 8
	s_cselect_b32 s40, 0x3140000, s42
	s_and_b64 s[34:35], s[34:35], exec
	s_cselect_b32 s61, 2, s43
	s_cmp_gt_u32 s91, 13
	s_cselect_b64 s[34:35], -1, 0
	s_mov_b32 s41, s99
	s_or_b64 s[34:35], s[34:35], s[36:37]
	s_lshl_b32 s36, s91, 3
	s_mov_b32 s37, s99
	v_lshl_add_u64 v[70:71], v[90:91], 0, s[40:41]
	s_lshl_b64 s[36:37], s[36:37], 2
	v_readlane_b32 s41, v251, 3
	s_add_u32 s36, s41, s36
	v_readlane_b32 s41, v251, 4
	s_addc_u32 s37, s41, s37
	s_lshl_b32 s64, s60, 7
	s_lshl_b32 s41, s60, 5
	s_lshl_b32 s52, s60, 6
	s_lshr_b32 s66, s60, 6
	s_and_b64 s[42:43], s[28:29], exec
	s_waitcnt vmcnt(3)
	v_and_b32_e32 v2, 15, v0
	v_ashrrev_i32_e32 v3, 1, v0
	s_movk_i32 s42, 0xffc0
	v_and_or_b32 v88, v3, s42, v2
	v_lshrrev_b32_e32 v2, 2, v0
	s_mul_i32 s53, s60, 0x60
	v_and_b32_e32 v2, 12, v2
	v_lshl_add_u64 v[68:69], v[90:91], 0, s[98:99]
	s_cselect_b32 s65, 17, 0
	v_and_or_b32 v89, v0, 64, v2
	v_mov_b32_e32 v67, v66
	s_add_i32 s66, s66, -1
	s_or_b32 s46, s98, 0x80
	s_mov_b32 s47, s99
	s_lshl_b32 s67, s60, 8
	s_lshl_b32 s68, s60, 1
	s_or_b32 s48, s40, 0x80
	s_mov_b32 s49, s99
	v_mov_b32_e32 v135, 0
	s_mov_b64 s[50:51], 0
	v_mov_b32_e32 v138, s39
	s_lshl_b32 s98, s41, 1
	s_lshl_b32 s52, s52, 1
	s_lshl_b32 s54, s53, 1
	s_waitcnt vmcnt(0) lgkmcnt(0)
	s_lshr_b32 s23, s23, 1
	s_load_dwordx2 s[60:61], s[0:1], 0x0
	s_load_dwordx2 s[64:65], s[0:1], 0x10
	s_movk_i32 s50, 0x1600
	s_mov_b32 s53, 0x8b80000
	s_mov_b32 s54, 0x1b80000
	s_mov_b32 s68, 0.5
	s_cmp_eq_u32 s77, 10
	s_cselect_b32 s50, 0x800, s50
	s_cselect_b32 s52, 7, 21
	s_cselect_b32 s53, 0x164a0000, s53
	s_cselect_b32 s54, 0x3140000, s54
	s_cselect_b32 s55, 5, 8
	s_cselect_b32 s68, 1.0, s68
	s_cmp_eq_u32 s77, 2
	s_cselect_b32 s54, 0x1600000, s54
	s_cselect_b32 s55, 2, s55
	s_cselect_b32 s57, 1, 0
	s_cmp_gt_u32 s91, 13
	s_cselect_b32 s56, 17, 0
	s_cselect_b32 s57, 0, s57
	s_lshl_b32 s51, s50, 5
	v_mov_b32_e32 v246, s68
	v_readfirstlane_b32 s40, v92
	v_readfirstlane_b32 s41, v93
	v_readfirstlane_b32 s42, v94
	v_readfirstlane_b32 s43, v95
	v_readfirstlane_b32 s44, v96
	v_readfirstlane_b32 s45, v97
	v_readfirstlane_b32 s46, v98
	v_readfirstlane_b32 s47, v99
	v_writelane_b32 v249, s40, 0
	v_writelane_b32 v249, s41, 1
	v_writelane_b32 v249, s42, 2
	v_writelane_b32 v249, s43, 3
	v_writelane_b32 v249, s44, 4
	v_writelane_b32 v249, s45, 5
	v_writelane_b32 v249, s46, 6
	v_writelane_b32 v249, s47, 7
	v_readfirstlane_b32 s40, v100
	v_readfirstlane_b32 s41, v101
	v_readfirstlane_b32 s42, v102
	v_readfirstlane_b32 s43, v103
	v_readfirstlane_b32 s44, v104
	v_readfirstlane_b32 s45, v105
	v_readfirstlane_b32 s46, v106
	v_readfirstlane_b32 s47, v107
	v_writelane_b32 v249, s40, 8
	v_writelane_b32 v249, s41, 9
	v_writelane_b32 v249, s42, 10
	v_writelane_b32 v249, s43, 11
	v_writelane_b32 v249, s44, 12
	v_writelane_b32 v249, s45, 13
	v_writelane_b32 v249, s46, 14
	v_writelane_b32 v249, s47, 15
	v_readfirstlane_b32 s40, v108
	v_readfirstlane_b32 s41, v109
	v_readfirstlane_b32 s42, v110
	v_readfirstlane_b32 s43, v111
	v_readfirstlane_b32 s44, v112
	v_readfirstlane_b32 s45, v113
	v_readfirstlane_b32 s46, v114
	v_readfirstlane_b32 s47, v115
	v_writelane_b32 v249, s40, 16
	v_writelane_b32 v249, s41, 17
	v_writelane_b32 v249, s42, 18
	v_writelane_b32 v249, s43, 19
	v_writelane_b32 v249, s44, 20
	v_writelane_b32 v249, s45, 21
	v_writelane_b32 v249, s46, 22
	v_writelane_b32 v249, s47, 23
	v_readfirstlane_b32 s40, v116
	v_readfirstlane_b32 s41, v117
	v_readfirstlane_b32 s42, v118
	v_readfirstlane_b32 s43, v119
	v_readfirstlane_b32 s44, v120
	v_readfirstlane_b32 s45, v121
	v_readfirstlane_b32 s46, v122
	v_readfirstlane_b32 s47, v123
	v_writelane_b32 v249, s40, 24
	v_writelane_b32 v249, s41, 25
	v_writelane_b32 v249, s42, 26
	v_writelane_b32 v249, s43, 27
	v_writelane_b32 v249, s44, 28
	v_writelane_b32 v249, s45, 29
	v_writelane_b32 v249, s46, 30
	v_writelane_b32 v249, s47, 31
	v_readfirstlane_b32 s40, v124
	v_readfirstlane_b32 s41, v125
	v_readfirstlane_b32 s42, v126
	v_readfirstlane_b32 s43, v127
	v_readfirstlane_b32 s44, v128
	v_readfirstlane_b32 s45, v129
	v_readfirstlane_b32 s46, v130
	v_readfirstlane_b32 s47, v131
	v_writelane_b32 v249, s40, 32
	v_writelane_b32 v249, s41, 33
	v_writelane_b32 v249, s42, 34
	v_writelane_b32 v249, s43, 35
	v_writelane_b32 v249, s44, 36
	v_writelane_b32 v249, s45, 37
	v_writelane_b32 v249, s46, 38
	v_writelane_b32 v249, s47, 39
	v_readfirstlane_b32 s40, v132
	v_readfirstlane_b32 s41, v133
	s_nop 1
	v_writelane_b32 v249, s40, 40
	v_writelane_b32 v249, s41, 41
	v_readfirstlane_b32 s100, v90
	v_readfirstlane_b32 s101, v91
	v_lshrrev_b32_e32 v238, 4, v172
	v_and_b32_e32 v238, 7, v238
	v_and_b32_e32 v239, 7, v172
	v_xor_b32_e32 v238, v238, v239
	v_lshlrev_b32_e32 v238, 4, v238
	v_lshrrev_b32_e32 v239, 3, v172
	v_lshl_or_b32 v228, v239, 11, v238
	v_and_b32_e32 v238, 15, v172
	v_lshrrev_b32_e32 v239, 1, v238
	v_and_b32_e32 v239, 7, v239
	v_bfe_u32 v240, v172, 4, 2
	v_xor_b32_e32 v239, v239, v240
	v_lshlrev_b32_e32 v239, 4, v239
	v_and_b32_e32 v240, 7, v238
	v_lshl_or_b32 v239, v240, 7, v239
	v_lshrrev_b32_e32 v240, 3, v238
	v_lshl_or_b32 v239, v240, 10, v239
	v_lshrrev_b32_e32 v240, 7, v172
	v_lshl_or_b32 v231, v240, 14, v239
	v_bfe_u32 v240, v172, 6, 1
	v_lshl_or_b32 v232, v240, 13, v239
	v_add_u32_e32 v232, 0x10000, v232
	v_xor_b32_e32 v235, 64, v231
	v_xor_b32_e32 v236, 64, v232
	v_readfirstlane_b32 s46, v172
	s_nop 3
	s_lshr_b32 s46, s46, 6
	s_lshl_b32 s46, s46, 10
	v_lshrrev_b32_e32 v238, 4, v172
	v_and_b32_e32 v238, 7, v238
	v_and_b32_e32 v239, 7, v172
	v_xor_b32_e32 v238, v238, v239
	v_lshlrev_b32_e32 v238, 4, v238
	v_lshrrev_b32_e32 v239, 3, v172
	v_mad_u32_u24 v228, v239, s50, v238
	v_bfe_u32 v239, v172, 6, 1
	v_bfe_u32 v240, v172, 4, 2
	v_lshlrev_b32_e32 v240, 4, v240
	v_lshl_or_b32 v237, v239, 8, v240
	v_lshrrev_b32_e32 v238, 7, v172
	v_and_b32_e32 v239, 15, v172
	v_lshl_or_b32 v238, v238, 7, v239
	v_lshl_or_b32 v234, v238, 12, v237
	s_waitcnt lgkmcnt(0)
	s_mov_b32 s44, s39

;     ...
; #pragma unroll
;   for (int i = 0; i < 4; ++i) __builtin_amdgcn_global_load_lds((const unsigned*)(ag + (size_t)(32 * i) * lda), (unsigned*)(smem + i * 4096 + o0), 16, 0, 0);
; #pragma unroll
;   for (int i = 0; i < NT; ++i) __builtin_amdgcn_global_load_lds((const unsigned*)(bg + (size_t)((i & 1) * bs1 + (i >> 1) * bs2) * ldb), (unsigned*)(smem + 16384 + i * 4096 + o0), 16, 0, 0);
;   asm volatile("s_waitcnt vmcnt(0)" ::: "memory");
;   __syncthreads();
;   for (int kt = 0; kt < nk; ++kt) {
;     const int cur = (kt & 1) * 32768, nxt = 32768 - cur;
;     if (kt + 1 < nk) {
; #pragma unroll
;       for (int i = 0; i < 4; ++i)
;         __builtin_amdgcn_global_load_lds((const unsigned*)(A8 + (size_t)(kt + 1) * 128 + aoff[i]), (unsigned*)(smem + nxt + i * 4096 + wbase), 16, 0, 0);
; #pragma unroll
;       for (int i = 0; i < NT; ++i)
;         __builtin_amdgcn_global_load_lds((const unsigned*)(B8 + (size_t)(kt + 1) * 128 + boff[i]), (unsigned*)(smem + nxt + 16384 + i * 4096 + wbase), 16, 0, 0);
;     }
;     __builtin_amdgcn_sched_barrier(0);
;     if (LEAN) {
; #pragma unroll
;       for (int ks = 0; ks < 2; ++ks) {
;         bf16x8 af[4], bfr[NT];
; #pragma unroll
;         for (int m = 0; m < 4; ++m) af[m] = *(const bf16x8*)(smem + cur + ((abase + m * 2048) ^ (ks * 64)));
; #pragma unroll
;         for (int n = 0; n < NT; ++n) bfr[n] = *(const bf16x8*)(smem + cur + ((bbase + n * 2048) ^ (ks * 64)));
;         __builtin_amdgcn_s_setprio(1);
; #pragma unroll
;         for (int m = 0; m < 4; ++m)
; #pragma unroll
;           for (int n = 0; n < NT; ++n) acc[m][n] = __builtin_amdgcn_mfma_f32_16x16x32_bf16(bfr[n], af[m], acc[m][n], 0, 0, 0);
; __device__ __forceinline__ void phase_resid_gemm(const Params& p, const bf16_t* A, int lda, const bf16_t* Wt, int K, int l, int gate_k, float scale,
;                                  bool from_input, int mrows, char* smem, unsigned* tk) {
;     ...
;   for (TileIter ti(mrows / 128, 8, 4, 8, tk); ti.valid();) {
;     int tm, tn; ti.get(tm, tn);
;     ti.prefetch();
;     f32x4 acc[4][4];
;     zero_acc<4>(acc);
;     gemm_main<4>(A + (size_t)tm * 128 * lda, lda, Wt + (size_t)tn * 128 * K, K, K, acc, smem);
.Lrs_tk0:
	s_or_b64 exec, exec, s[48:49]
	s_lshr_b32 s45, s44, 4
	s_and_b32 s48, s44, 15
	s_lshl_b32 s45, s45, 3
	s_add_i32 s45, s45, s72
	s_lshl_b32 s47, s45, 1
	s_lshr_b32 s45, s48, 3
	s_add_i32 s47, s47, s45
	s_and_b32 s98, s48, 7
	s_lshl_b32 s45, s50, 8
	s_mul_i32 s45, s45, s47
	s_add_u32 s40, s100, s53
	s_addc_u32 s41, s101, 0
	s_add_u32 s40, s40, s45
	s_addc_u32 s41, s41, 0
	s_lshl_b32 s45, s50, 7
	s_mul_i32 s45, s45, s98
	s_add_u32 s42, s100, s54
	s_addc_u32 s43, s101, 0
	s_add_u32 s42, s42, s45
	s_addc_u32 s43, s43, 0
	s_add_i32 m0, s46, 0x0
	s_nop 0
	global_load_lds_dwordx4 v228, s[40:41]
	v_add_u32_e32 v230, s51, v228
	s_add_i32 m0, s46, 0x1000
	s_nop 0
	global_load_lds_dwordx4 v230, s[40:41]
	v_add_u32_e32 v230, s51, v230
	s_add_i32 m0, s46, 0x2000
	s_nop 0
	global_load_lds_dwordx4 v230, s[40:41]
	v_add_u32_e32 v230, s51, v230
	s_add_i32 m0, s46, 0x3000
	s_nop 0
	global_load_lds_dwordx4 v230, s[40:41]
	v_add_u32_e32 v230, s51, v230
	s_add_i32 m0, s46, 0x4000
	s_nop 0
	global_load_lds_dwordx4 v230, s[40:41]
	v_add_u32_e32 v230, s51, v230
	s_add_i32 m0, s46, 0x5000
	s_nop 0
	global_load_lds_dwordx4 v230, s[40:41]
	v_add_u32_e32 v230, s51, v230
	s_add_i32 m0, s46, 0x6000
	s_nop 0
	global_load_lds_dwordx4 v230, s[40:41]
	v_add_u32_e32 v230, s51, v230
	s_add_i32 m0, s46, 0x7000
	s_nop 0
	global_load_lds_dwordx4 v230, s[40:41]
	s_add_i32 m0, s46, 0x10000
	s_nop 0
	global_load_lds_dwordx4 v228, s[42:43]
	v_add_u32_e32 v230, s51, v228
	s_add_i32 m0, s46, 0x11000
	s_nop 0
	global_load_lds_dwordx4 v230, s[42:43]
	v_add_u32_e32 v230, s51, v230
	s_add_i32 m0, s46, 0x12000
	s_nop 0
	global_load_lds_dwordx4 v230, s[42:43]
	v_add_u32_e32 v230, s51, v230
	s_add_i32 m0, s46, 0x13000
	s_nop 0
	global_load_lds_dwordx4 v230, s[42:43]
	v_mov_b64_e32 v[2:3], 0
	v_mov_b64_e32 v[4:5], 0
	v_mov_b64_e32 v[6:7], 0
	v_mov_b64_e32 v[8:9], 0
	v_mov_b64_e32 v[10:11], 0
	v_mov_b64_e32 v[12:13], 0
	v_mov_b64_e32 v[14:15], 0
	v_mov_b64_e32 v[16:17], 0
	v_mov_b64_e32 v[18:19], 0
	v_mov_b64_e32 v[20:21], 0
	v_mov_b64_e32 v[22:23], 0
	v_mov_b64_e32 v[24:25], 0
	v_mov_b64_e32 v[26:27], 0
	v_mov_b64_e32 v[28:29], 0
	v_mov_b64_e32 v[30:31], 0
	v_mov_b64_e32 v[32:33], 0
	v_mov_b64_e32 v[34:35], 0
	v_mov_b64_e32 v[36:37], 0
	v_mov_b64_e32 v[38:39], 0
	v_mov_b64_e32 v[40:41], 0
	v_mov_b64_e32 v[42:43], 0
	v_mov_b64_e32 v[44:45], 0
	v_mov_b64_e32 v[46:47], 0
	v_mov_b64_e32 v[48:49], 0
	v_mov_b64_e32 v[50:51], 0
	v_mov_b64_e32 v[52:53], 0
	v_mov_b64_e32 v[54:55], 0
	v_mov_b64_e32 v[56:57], 0
	v_mov_b64_e32 v[58:59], 0
	v_mov_b64_e32 v[60:61], 0
	v_mov_b64_e32 v[62:63], 0
	v_mov_b64_e32 v[64:65], 0
	v_mov_b64_e32 v[66:67], 0
	v_mov_b64_e32 v[68:69], 0
	v_mov_b64_e32 v[70:71], 0
	v_mov_b64_e32 v[72:73], 0
	v_mov_b64_e32 v[74:75], 0
	v_mov_b64_e32 v[76:77], 0
	v_mov_b64_e32 v[78:79], 0
	v_mov_b64_e32 v[80:81], 0
	v_mov_b64_e32 v[82:83], 0
	v_mov_b64_e32 v[84:85], 0
	v_mov_b64_e32 v[86:87], 0
	v_mov_b64_e32 v[88:89], 0
	v_mov_b64_e32 v[92:93], 0
	v_mov_b64_e32 v[94:95], 0
	v_mov_b64_e32 v[96:97], 0
	v_mov_b64_e32 v[98:99], 0
	v_mov_b64_e32 v[100:101], 0
	v_mov_b64_e32 v[102:103], 0
	v_mov_b64_e32 v[104:105], 0
	v_mov_b64_e32 v[106:107], 0
	v_mov_b64_e32 v[108:109], 0
	v_mov_b64_e32 v[110:111], 0
	v_mov_b64_e32 v[112:113], 0
	v_mov_b64_e32 v[114:115], 0
	v_mov_b64_e32 v[116:117], 0
	v_mov_b64_e32 v[118:119], 0
	v_mov_b64_e32 v[120:121], 0
	v_mov_b64_e32 v[122:123], 0
	v_mov_b64_e32 v[124:125], 0
	v_mov_b64_e32 v[126:127], 0
	v_mov_b64_e32 v[128:129], 0
	v_mov_b64_e32 v[130:131], 0
	s_waitcnt vmcnt(0)
	s_barrier
	s_mov_b32 s45, s52
.Lrs_kloop:
	ds_read_b128 v[136:139], v232
	ds_read_b128 v[140:143], v232 offset:2048
	ds_read_b128 v[144:147], v232 offset:4096
	ds_read_b128 v[148:151], v232 offset:6144
	ds_read_b128 v[196:199], v231
	ds_read_b128 v[200:203], v231 offset:2048
	ds_read_b128 v[204:207], v231 offset:4096
	ds_read_b128 v[208:211], v231 offset:6144
	ds_read_b128 v[152:155], v236
	ds_read_b128 v[156:159], v236 offset:2048
	ds_read_b128 v[160:163], v236 offset:4096
	ds_read_b128 v[164:167], v236 offset:6144
	ds_read_b128 v[212:215], v231 offset:8192
	ds_read_b128 v[216:219], v231 offset:10240
	ds_read_b128 v[220:223], v231 offset:12288
	ds_read_b128 v[224:227], v231 offset:14336
	s_setprio 1
	s_waitcnt lgkmcnt(8)
	v_mfma_f32_16x16x32_bf16 v[2:5], v[136:139], v[196:199], v[2:5]
	v_mfma_f32_16x16x32_bf16 v[6:9], v[140:143], v[196:199], v[6:9]
	v_mfma_f32_16x16x32_bf16 v[10:13], v[144:147], v[196:199], v[10:13]
	v_mfma_f32_16x16x32_bf16 v[14:17], v[148:151], v[196:199], v[14:17]
	v_mfma_f32_16x16x32_bf16 v[18:21], v[136:139], v[200:203], v[18:21]
	v_mfma_f32_16x16x32_bf16 v[22:25], v[140:143], v[200:203], v[22:25]
	v_mfma_f32_16x16x32_bf16 v[26:29], v[144:147], v[200:203], v[26:29]
	v_mfma_f32_16x16x32_bf16 v[30:33], v[148:151], v[200:203], v[30:33]
	v_mfma_f32_16x16x32_bf16 v[34:37], v[136:139], v[204:207], v[34:37]
	v_mfma_f32_16x16x32_bf16 v[38:41], v[140:143], v[204:207], v[38:41]
	v_mfma_f32_16x16x32_bf16 v[42:45], v[144:147], v[204:207], v[42:45]
	v_mfma_f32_16x16x32_bf16 v[46:49], v[148:151], v[204:207], v[46:49]
	v_mfma_f32_16x16x32_bf16 v[50:53], v[136:139], v[208:211], v[50:53]
	v_mfma_f32_16x16x32_bf16 v[54:57], v[140:143], v[208:211], v[54:57]
	v_mfma_f32_16x16x32_bf16 v[58:61], v[144:147], v[208:211], v[58:61]
	v_mfma_f32_16x16x32_bf16 v[62:65], v[148:151], v[208:211], v[62:65]
	s_waitcnt lgkmcnt(0)
	s_barrier
;     ...
;   for (int kt = 0; kt < nk; ++kt) {
;     const int cur = (kt & 1) * 32768, nxt = 32768 - cur;
;     if (kt + 1 < nk) {
; #pragma unroll
;       for (int i = 0; i < 4; ++i)
;         __builtin_amdgcn_global_load_lds((const unsigned*)(A8 + (size_t)(kt + 1) * 128 + aoff[i]), (unsigned*)(smem + nxt + i * 4096 + wbase), 16, 0, 0);
; #pragma unroll
;       for (int i = 0; i < NT; ++i)
;         __builtin_amdgcn_global_load_lds((const unsigned*)(B8 + (size_t)(kt + 1) * 128 + boff[i]), (unsigned*)(smem + nxt + 16384 + i * 4096 + wbase), 16, 0, 0);
;     }
;     __builtin_amdgcn_sched_barrier(0);
;     if (LEAN) {
; #pragma unroll
;       for (int ks = 0; ks < 2; ++ks) {
;         bf16x8 af[4], bfr[NT];
; #pragma unroll
;         for (int m = 0; m < 4; ++m) af[m] = *(const bf16x8*)(smem + cur + ((abase + m * 2048) ^ (ks * 64)));
; #pragma unroll
;         for (int n = 0; n < NT; ++n) bfr[n] = *(const bf16x8*)(smem + cur + ((bbase + n * 2048) ^ (ks * 64)));
;         __builtin_amdgcn_s_setprio(1);
; #pragma unroll
;         for (int m = 0; m < 4; ++m)
; #pragma unroll
;           for (int n = 0; n < NT; ++n) acc[m][n] = __builtin_amdgcn_mfma_f32_16x16x32_bf16(bfr[n], af[m], acc[m][n], 0, 0, 0);
;         __builtin_amdgcn_s_setprio(0);
;       }
	s_add_u32 s40, s40, 0x80
	s_addc_u32 s41, s41, 0
	s_add_u32 s42, s42, 0x80
	s_addc_u32 s43, s43, 0
	ds_read_b128 v[196:199], v235
	ds_read_b128 v[200:203], v235 offset:2048
	ds_read_b128 v[204:207], v235 offset:4096
	ds_read_b128 v[208:211], v235 offset:6144
	s_add_i32 m0, s46, 0x8000
	v_mfma_f32_16x16x32_bf16 v[66:69], v[136:139], v[212:215], v[66:69]
	global_load_lds_dwordx4 v228, s[40:41]
	v_add_u32_e32 v230, s51, v228
	s_add_i32 m0, s46, 0x9000
	v_mfma_f32_16x16x32_bf16 v[70:73], v[140:143], v[212:215], v[70:73]
	global_load_lds_dwordx4 v230, s[40:41]
	v_add_u32_e32 v230, s51, v230
	s_add_i32 m0, s46, 0xa000
	v_mfma_f32_16x16x32_bf16 v[74:77], v[144:147], v[212:215], v[74:77]
	global_load_lds_dwordx4 v230, s[40:41]
	v_add_u32_e32 v230, s51, v230
	s_add_i32 m0, s46, 0xb000
	v_mfma_f32_16x16x32_bf16 v[78:81], v[148:151], v[212:215], v[78:81]
	global_load_lds_dwordx4 v230, s[40:41]
	v_add_u32_e32 v230, s51, v230
	s_add_i32 m0, s46, 0xc000
	v_mfma_f32_16x16x32_bf16 v[82:85], v[136:139], v[216:219], v[82:85]
	global_load_lds_dwordx4 v230, s[40:41]
	v_add_u32_e32 v230, s51, v230
	s_add_i32 m0, s46, 0xd000
	v_mfma_f32_16x16x32_bf16 v[86:89], v[140:143], v[216:219], v[86:89]
	global_load_lds_dwordx4 v230, s[40:41]
	v_add_u32_e32 v230, s51, v230
	s_add_i32 m0, s46, 0xe000
	v_mfma_f32_16x16x32_bf16 v[92:95], v[144:147], v[216:219], v[92:95]
	global_load_lds_dwordx4 v230, s[40:41]
	v_add_u32_e32 v230, s51, v230
	s_add_i32 m0, s46, 0xf000
	v_mfma_f32_16x16x32_bf16 v[96:99], v[148:151], v[216:219], v[96:99]
	global_load_lds_dwordx4 v230, s[40:41]
	s_add_i32 m0, s46, 0x10000
	v_mfma_f32_16x16x32_bf16 v[100:103], v[136:139], v[220:223], v[100:103]
	global_load_lds_dwordx4 v228, s[42:43]
	v_add_u32_e32 v230, s51, v228
	s_add_i32 m0, s46, 0x11000
	v_mfma_f32_16x16x32_bf16 v[104:107], v[140:143], v[220:223], v[104:107]
	global_load_lds_dwordx4 v230, s[42:43]
	v_add_u32_e32 v230, s51, v230
	s_add_i32 m0, s46, 0x12000
	v_mfma_f32_16x16x32_bf16 v[108:111], v[144:147], v[220:223], v[108:111]
	global_load_lds_dwordx4 v230, s[42:43]
	v_add_u32_e32 v230, s51, v230
	s_add_i32 m0, s46, 0x13000
	v_mfma_f32_16x16x32_bf16 v[112:115], v[148:151], v[220:223], v[112:115]
	global_load_lds_dwordx4 v230, s[42:43]
	v_mfma_f32_16x16x32_bf16 v[116:119], v[136:139], v[224:227], v[116:119]
	v_mfma_f32_16x16x32_bf16 v[120:123], v[140:143], v[224:227], v[120:123]
	v_mfma_f32_16x16x32_bf16 v[124:127], v[144:147], v[224:227], v[124:127]
	v_mfma_f32_16x16x32_bf16 v[128:131], v[148:151], v[224:227], v[128:131]
	ds_read_b128 v[212:215], v235 offset:8192
	ds_read_b128 v[216:219], v235 offset:10240
	ds_read_b128 v[220:223], v235 offset:12288
	ds_read_b128 v[224:227], v235 offset:14336
	s_waitcnt lgkmcnt(4)
	v_mfma_f32_16x16x32_bf16 v[2:5], v[152:155], v[196:199], v[2:5]
	v_mfma_f32_16x16x32_bf16 v[6:9], v[156:159], v[196:199], v[6:9]
	v_mfma_f32_16x16x32_bf16 v[10:13], v[160:163], v[196:199], v[10:13]
	v_mfma_f32_16x16x32_bf16 v[14:17], v[164:167], v[196:199], v[14:17]
	v_mfma_f32_16x16x32_bf16 v[18:21], v[152:155], v[200:203], v[18:21]
	v_mfma_f32_16x16x32_bf16 v[22:25], v[156:159], v[200:203], v[22:25]
	v_mfma_f32_16x16x32_bf16 v[26:29], v[160:163], v[200:203], v[26:29]
	v_mfma_f32_16x16x32_bf16 v[30:33], v[164:167], v[200:203], v[30:33]
	v_mfma_f32_16x16x32_bf16 v[34:37], v[152:155], v[204:207], v[34:37]
	v_mfma_f32_16x16x32_bf16 v[38:41], v[156:159], v[204:207], v[38:41]
	v_mfma_f32_16x16x32_bf16 v[42:45], v[160:163], v[204:207], v[42:45]
	v_mfma_f32_16x16x32_bf16 v[46:49], v[164:167], v[204:207], v[46:49]
	v_mfma_f32_16x16x32_bf16 v[50:53], v[152:155], v[208:211], v[50:53]
	v_mfma_f32_16x16x32_bf16 v[54:57], v[156:159], v[208:211], v[54:57]
	v_mfma_f32_16x16x32_bf16 v[58:61], v[160:163], v[208:211], v[58:61]
	v_mfma_f32_16x16x32_bf16 v[62:65], v[164:167], v[208:211], v[62:65]
	s_waitcnt lgkmcnt(0)
	v_mfma_f32_16x16x32_bf16 v[66:69], v[152:155], v[212:215], v[66:69]
	v_mfma_f32_16x16x32_bf16 v[70:73], v[156:159], v[212:215], v[70:73]
	v_mfma_f32_16x16x32_bf16 v[74:77], v[160:163], v[212:215], v[74:77]
	v_mfma_f32_16x16x32_bf16 v[78:81], v[164:167], v[212:215], v[78:81]
	v_mfma_f32_16x16x32_bf16 v[82:85], v[152:155], v[216:219], v[82:85]
	v_mfma_f32_16x16x32_bf16 v[86:89], v[156:159], v[216:219], v[86:89]
	v_mfma_f32_16x16x32_bf16 v[92:95], v[160:163], v[216:219], v[92:95]
	v_mfma_f32_16x16x32_bf16 v[96:99], v[164:167], v[216:219], v[96:99]
	v_mfma_f32_16x16x32_bf16 v[100:103], v[152:155], v[220:223], v[100:103]
	v_mfma_f32_16x16x32_bf16 v[104:107], v[156:159], v[220:223], v[104:107]
	v_mfma_f32_16x16x32_bf16 v[108:111], v[160:163], v[220:223], v[108:111]
	v_mfma_f32_16x16x32_bf16 v[112:115], v[164:167], v[220:223], v[112:115]
	v_mfma_f32_16x16x32_bf16 v[116:119], v[152:155], v[224:227], v[116:119]
	v_mfma_f32_16x16x32_bf16 v[120:123], v[156:159], v[224:227], v[120:123]
	v_mfma_f32_16x16x32_bf16 v[124:127], v[160:163], v[224:227], v[124:127]
	v_mfma_f32_16x16x32_bf16 v[128:131], v[164:167], v[224:227], v[128:131]
	s_setprio 0
	s_waitcnt vmcnt(0)
	s_barrier
;     ...
;   for (int kt = 0; kt < nk; ++kt) {
;     const int cur = (kt & 1) * 32768, nxt = 32768 - cur;
;     if (kt + 1 < nk) {
; #pragma unroll
;       for (int i = 0; i < 4; ++i)
;         __builtin_amdgcn_global_load_lds((const unsigned*)(A8 + (size_t)(kt + 1) * 128 + aoff[i]), (unsigned*)(smem + nxt + i * 4096 + wbase), 16, 0, 0);
; #pragma unroll
;       for (int i = 0; i < NT; ++i)
;         __builtin_amdgcn_global_load_lds((const unsigned*)(B8 + (size_t)(kt + 1) * 128 + boff[i]), (unsigned*)(smem + nxt + 16384 + i * 4096 + wbase), 16, 0, 0);
;     }
;     __builtin_amdgcn_sched_barrier(0);
;     if (LEAN) {
; #pragma unroll
;       for (int ks = 0; ks < 2; ++ks) {
;         bf16x8 af[4], bfr[NT];
; #pragma unroll
;         for (int m = 0; m < 4; ++m) af[m] = *(const bf16x8*)(smem + cur + ((abase + m * 2048) ^ (ks * 64)));
; #pragma unroll
;         for (int n = 0; n < NT; ++n) bfr[n] = *(const bf16x8*)(smem + cur + ((bbase + n * 2048) ^ (ks * 64)));
;         __builtin_amdgcn_s_setprio(1);
; #pragma unroll
;         for (int m = 0; m < 4; ++m)
; #pragma unroll
;           for (int n = 0; n < NT; ++n) acc[m][n] = __builtin_amdgcn_mfma_f32_16x16x32_bf16(bfr[n], af[m], acc[m][n], 0, 0, 0);
;         __builtin_amdgcn_s_setprio(0);
;       }
	ds_read_b128 v[136:139], v232
	ds_read_b128 v[140:143], v232 offset:2048
	ds_read_b128 v[144:147], v232 offset:4096
	ds_read_b128 v[148:151], v232 offset:6144
	ds_read_b128 v[196:199], v231 offset:32768
	ds_read_b128 v[200:203], v231 offset:34816
	ds_read_b128 v[204:207], v231 offset:36864
	ds_read_b128 v[208:211], v231 offset:38912
	ds_read_b128 v[152:155], v236
	ds_read_b128 v[156:159], v236 offset:2048
	ds_read_b128 v[160:163], v236 offset:4096
	ds_read_b128 v[164:167], v236 offset:6144
	ds_read_b128 v[212:215], v231 offset:40960
	ds_read_b128 v[216:219], v231 offset:43008
	ds_read_b128 v[220:223], v231 offset:45056
	ds_read_b128 v[224:227], v231 offset:47104
	s_setprio 1
	s_waitcnt lgkmcnt(8)
	v_mfma_f32_16x16x32_bf16 v[2:5], v[136:139], v[196:199], v[2:5]
	v_mfma_f32_16x16x32_bf16 v[6:9], v[140:143], v[196:199], v[6:9]
	v_mfma_f32_16x16x32_bf16 v[10:13], v[144:147], v[196:199], v[10:13]
	v_mfma_f32_16x16x32_bf16 v[14:17], v[148:151], v[196:199], v[14:17]
	v_mfma_f32_16x16x32_bf16 v[18:21], v[136:139], v[200:203], v[18:21]
	v_mfma_f32_16x16x32_bf16 v[22:25], v[140:143], v[200:203], v[22:25]
	v_mfma_f32_16x16x32_bf16 v[26:29], v[144:147], v[200:203], v[26:29]
	v_mfma_f32_16x16x32_bf16 v[30:33], v[148:151], v[200:203], v[30:33]
	v_mfma_f32_16x16x32_bf16 v[34:37], v[136:139], v[204:207], v[34:37]
	v_mfma_f32_16x16x32_bf16 v[38:41], v[140:143], v[204:207], v[38:41]
	v_mfma_f32_16x16x32_bf16 v[42:45], v[144:147], v[204:207], v[42:45]
	v_mfma_f32_16x16x32_bf16 v[46:49], v[148:151], v[204:207], v[46:49]
	v_mfma_f32_16x16x32_bf16 v[50:53], v[136:139], v[208:211], v[50:53]
	v_mfma_f32_16x16x32_bf16 v[54:57], v[140:143], v[208:211], v[54:57]
	v_mfma_f32_16x16x32_bf16 v[58:61], v[144:147], v[208:211], v[58:61]
	v_mfma_f32_16x16x32_bf16 v[62:65], v[148:151], v[208:211], v[62:65]
	s_waitcnt lgkmcnt(0)
	s_barrier
	s_add_u32 s40, s40, 0x80
	s_addc_u32 s41, s41, 0
	s_add_u32 s42, s42, 0x80
	s_addc_u32 s43, s43, 0
	ds_read_b128 v[196:199], v235 offset:32768
	ds_read_b128 v[200:203], v235 offset:34816
	ds_read_b128 v[204:207], v235 offset:36864
	ds_read_b128 v[208:211], v235 offset:38912
	s_add_i32 m0, s46, 0x0
	v_mfma_f32_16x16x32_bf16 v[66:69], v[136:139], v[212:215], v[66:69]
	global_load_lds_dwordx4 v228, s[40:41]
	v_add_u32_e32 v230, s51, v228
	s_add_i32 m0, s46, 0x1000
	v_mfma_f32_16x16x32_bf16 v[70:73], v[140:143], v[212:215], v[70:73]
	global_load_lds_dwordx4 v230, s[40:41]
	v_add_u32_e32 v230, s51, v230
	s_add_i32 m0, s46, 0x2000
	v_mfma_f32_16x16x32_bf16 v[74:77], v[144:147], v[212:215], v[74:77]
	global_load_lds_dwordx4 v230, s[40:41]
	v_add_u32_e32 v230, s51, v230
	s_add_i32 m0, s46, 0x3000
	v_mfma_f32_16x16x32_bf16 v[78:81], v[148:151], v[212:215], v[78:81]
	global_load_lds_dwordx4 v230, s[40:41]
	v_add_u32_e32 v230, s51, v230
	s_add_i32 m0, s46, 0x4000
	v_mfma_f32_16x16x32_bf16 v[82:85], v[136:139], v[216:219], v[82:85]
	global_load_lds_dwordx4 v230, s[40:41]
	v_add_u32_e32 v230, s51, v230
	s_add_i32 m0, s46, 0x5000
	v_mfma_f32_16x16x32_bf16 v[86:89], v[140:143], v[216:219], v[86:89]
	global_load_lds_dwordx4 v230, s[40:41]
	v_add_u32_e32 v230, s51, v230
	s_add_i32 m0, s46, 0x6000
	v_mfma_f32_16x16x32_bf16 v[92:95], v[144:147], v[216:219], v[92:95]
	global_load_lds_dwordx4 v230, s[40:41]
	v_add_u32_e32 v230, s51, v230
	s_add_i32 m0, s46, 0x7000
	v_mfma_f32_16x16x32_bf16 v[96:99], v[148:151], v[216:219], v[96:99]
	global_load_lds_dwordx4 v230, s[40:41]
	s_add_i32 m0, s46, 0x10000
	v_mfma_f32_16x16x32_bf16 v[100:103], v[136:139], v[220:223], v[100:103]
	global_load_lds_dwordx4 v228, s[42:43]
	v_add_u32_e32 v230, s51, v228
	s_add_i32 m0, s46, 0x11000
	v_mfma_f32_16x16x32_bf16 v[104:107], v[140:143], v[220:223], v[104:107]
	global_load_lds_dwordx4 v230, s[42:43]
	v_add_u32_e32 v230, s51, v230
	s_add_i32 m0, s46, 0x12000
	v_mfma_f32_16x16x32_bf16 v[108:111], v[144:147], v[220:223], v[108:111]
	global_load_lds_dwordx4 v230, s[42:43]
	v_add_u32_e32 v230, s51, v230
	s_add_i32 m0, s46, 0x13000
	v_mfma_f32_16x16x32_bf16 v[112:115], v[148:151], v[220:223], v[112:115]
	global_load_lds_dwordx4 v230, s[42:43]
	v_mfma_f32_16x16x32_bf16 v[116:119], v[136:139], v[224:227], v[116:119]
	v_mfma_f32_16x16x32_bf16 v[120:123], v[140:143], v[224:227], v[120:123]
	v_mfma_f32_16x16x32_bf16 v[124:127], v[144:147], v[224:227], v[124:127]
	v_mfma_f32_16x16x32_bf16 v[128:131], v[148:151], v[224:227], v[128:131]
	ds_read_b128 v[212:215], v235 offset:40960
	ds_read_b128 v[216:219], v235 offset:43008
	ds_read_b128 v[220:223], v235 offset:45056
	ds_read_b128 v[224:227], v235 offset:47104
	s_waitcnt lgkmcnt(4)
	v_mfma_f32_16x16x32_bf16 v[2:5], v[152:155], v[196:199], v[2:5]
	v_mfma_f32_16x16x32_bf16 v[6:9], v[156:159], v[196:199], v[6:9]
	v_mfma_f32_16x16x32_bf16 v[10:13], v[160:163], v[196:199], v[10:13]
	v_mfma_f32_16x16x32_bf16 v[14:17], v[164:167], v[196:199], v[14:17]
	v_mfma_f32_16x16x32_bf16 v[18:21], v[152:155], v[200:203], v[18:21]
	v_mfma_f32_16x16x32_bf16 v[22:25], v[156:159], v[200:203], v[22:25]
	v_mfma_f32_16x16x32_bf16 v[26:29], v[160:163], v[200:203], v[26:29]
	v_mfma_f32_16x16x32_bf16 v[30:33], v[164:167], v[200:203], v[30:33]
	v_mfma_f32_16x16x32_bf16 v[34:37], v[152:155], v[204:207], v[34:37]
	v_mfma_f32_16x16x32_bf16 v[38:41], v[156:159], v[204:207], v[38:41]
	v_mfma_f32_16x16x32_bf16 v[42:45], v[160:163], v[204:207], v[42:45]
	v_mfma_f32_16x16x32_bf16 v[46:49], v[164:167], v[204:207], v[46:49]
	v_mfma_f32_16x16x32_bf16 v[50:53], v[152:155], v[208:211], v[50:53]
	v_mfma_f32_16x16x32_bf16 v[54:57], v[156:159], v[208:211], v[54:57]
	v_mfma_f32_16x16x32_bf16 v[58:61], v[160:163], v[208:211], v[58:61]
	v_mfma_f32_16x16x32_bf16 v[62:65], v[164:167], v[208:211], v[62:65]
	s_waitcnt lgkmcnt(0)
	v_mfma_f32_16x16x32_bf16 v[66:69], v[152:155], v[212:215], v[66:69]
	v_mfma_f32_16x16x32_bf16 v[70:73], v[156:159], v[212:215], v[70:73]
	v_mfma_f32_16x16x32_bf16 v[74:77], v[160:163], v[212:215], v[74:77]
	v_mfma_f32_16x16x32_bf16 v[78:81], v[164:167], v[212:215], v[78:81]
	v_mfma_f32_16x16x32_bf16 v[82:85], v[152:155], v[216:219], v[82:85]
	v_mfma_f32_16x16x32_bf16 v[86:89], v[156:159], v[216:219], v[86:89]
	v_mfma_f32_16x16x32_bf16 v[92:95], v[160:163], v[216:219], v[92:95]
	v_mfma_f32_16x16x32_bf16 v[96:99], v[164:167], v[216:219], v[96:99]
	v_mfma_f32_16x16x32_bf16 v[100:103], v[152:155], v[220:223], v[100:103]
	v_mfma_f32_16x16x32_bf16 v[104:107], v[156:159], v[220:223], v[104:107]
	v_mfma_f32_16x16x32_bf16 v[108:111], v[160:163], v[220:223], v[108:111]
	v_mfma_f32_16x16x32_bf16 v[112:115], v[164:167], v[220:223], v[112:115]
	v_mfma_f32_16x16x32_bf16 v[116:119], v[152:155], v[224:227], v[116:119]
	v_mfma_f32_16x16x32_bf16 v[120:123], v[156:159], v[224:227], v[120:123]
	v_mfma_f32_16x16x32_bf16 v[124:127], v[160:163], v[224:227], v[124:127]
	v_mfma_f32_16x16x32_bf16 v[128:131], v[164:167], v[224:227], v[128:131]
	s_setprio 0
	s_waitcnt vmcnt(0)
	s_barrier
;     ...
;   for (int kt = 0; kt < nk; ++kt) {
;     const int cur = (kt & 1) * 32768, nxt = 32768 - cur;
;     if (kt + 1 < nk) {
; #pragma unroll
;       for (int i = 0; i < 4; ++i)
;         __builtin_amdgcn_global_load_lds((const unsigned*)(A8 + (size_t)(kt + 1) * 128 + aoff[i]), (unsigned*)(smem + nxt + i * 4096 + wbase), 16, 0, 0);
; #pragma unroll
;       for (int i = 0; i < NT; ++i)
;         __builtin_amdgcn_global_load_lds((const unsigned*)(B8 + (size_t)(kt + 1) * 128 + boff[i]), (unsigned*)(smem + nxt + 16384 + i * 4096 + wbase), 16, 0, 0);
;     }
;     __builtin_amdgcn_sched_barrier(0);
;     if (LEAN) {
; #pragma unroll
;       for (int ks = 0; ks < 2; ++ks) {
;         bf16x8 af[4], bfr[NT];
; #pragma unroll
;         for (int m = 0; m < 4; ++m) af[m] = *(const bf16x8*)(smem + cur + ((abase + m * 2048) ^ (ks * 64)));
; #pragma unroll
;         for (int n = 0; n < NT; ++n) bfr[n] = *(const bf16x8*)(smem + cur + ((bbase + n * 2048) ^ (ks * 64)));
;         __builtin_amdgcn_s_setprio(1);
; #pragma unroll
;         for (int m = 0; m < 4; ++m)
; #pragma unroll
;           for (int n = 0; n < NT; ++n) acc[m][n] = __builtin_amdgcn_mfma_f32_16x16x32_bf16(bfr[n], af[m], acc[m][n], 0, 0, 0);
;         __builtin_amdgcn_s_setprio(0);
;       }
	s_add_i32 s45, s45, -1
	s_cmp_lg_u32 s45, 0
	s_cbranch_scc1 .Lrs_kloop
	ds_read_b128 v[136:139], v232
	ds_read_b128 v[140:143], v232 offset:2048
	ds_read_b128 v[144:147], v232 offset:4096
	ds_read_b128 v[148:151], v232 offset:6144
	ds_read_b128 v[196:199], v231
	ds_read_b128 v[200:203], v231 offset:2048
	ds_read_b128 v[204:207], v231 offset:4096
	ds_read_b128 v[208:211], v231 offset:6144
	ds_read_b128 v[152:155], v236
	ds_read_b128 v[156:159], v236 offset:2048
	ds_read_b128 v[160:163], v236 offset:4096
	ds_read_b128 v[164:167], v236 offset:6144
	ds_read_b128 v[212:215], v231 offset:8192
	ds_read_b128 v[216:219], v231 offset:10240
	ds_read_b128 v[220:223], v231 offset:12288
	ds_read_b128 v[224:227], v231 offset:14336
	s_setprio 1
	s_waitcnt lgkmcnt(8)
	v_mfma_f32_16x16x32_bf16 v[2:5], v[136:139], v[196:199], v[2:5]
	v_mfma_f32_16x16x32_bf16 v[6:9], v[140:143], v[196:199], v[6:9]
	v_mfma_f32_16x16x32_bf16 v[10:13], v[144:147], v[196:199], v[10:13]
	v_mfma_f32_16x16x32_bf16 v[14:17], v[148:151], v[196:199], v[14:17]
	v_mfma_f32_16x16x32_bf16 v[18:21], v[136:139], v[200:203], v[18:21]
	v_mfma_f32_16x16x32_bf16 v[22:25], v[140:143], v[200:203], v[22:25]
	v_mfma_f32_16x16x32_bf16 v[26:29], v[144:147], v[200:203], v[26:29]
	v_mfma_f32_16x16x32_bf16 v[30:33], v[148:151], v[200:203], v[30:33]
	v_mfma_f32_16x16x32_bf16 v[34:37], v[136:139], v[204:207], v[34:37]
	v_mfma_f32_16x16x32_bf16 v[38:41], v[140:143], v[204:207], v[38:41]
	v_mfma_f32_16x16x32_bf16 v[42:45], v[144:147], v[204:207], v[42:45]
	v_mfma_f32_16x16x32_bf16 v[46:49], v[148:151], v[204:207], v[46:49]
	v_mfma_f32_16x16x32_bf16 v[50:53], v[136:139], v[208:211], v[50:53]
	v_mfma_f32_16x16x32_bf16 v[54:57], v[140:143], v[208:211], v[54:57]
	v_mfma_f32_16x16x32_bf16 v[58:61], v[144:147], v[208:211], v[58:61]
	v_mfma_f32_16x16x32_bf16 v[62:65], v[148:151], v[208:211], v[62:65]
	s_waitcnt lgkmcnt(0)
	s_barrier
	s_add_u32 s40, s40, 0x80
	s_addc_u32 s41, s41, 0
	s_add_u32 s42, s42, 0x80
	s_addc_u32 s43, s43, 0
	ds_read_b128 v[196:199], v235
	ds_read_b128 v[200:203], v235 offset:2048
	ds_read_b128 v[204:207], v235 offset:4096
	ds_read_b128 v[208:211], v235 offset:6144
	s_add_i32 m0, s46, 0x8000
	v_mfma_f32_16x16x32_bf16 v[66:69], v[136:139], v[212:215], v[66:69]
	global_load_lds_dwordx4 v228, s[40:41]
	v_add_u32_e32 v230, s51, v228
	s_add_i32 m0, s46, 0x9000
	v_mfma_f32_16x16x32_bf16 v[70:73], v[140:143], v[212:215], v[70:73]
	global_load_lds_dwordx4 v230, s[40:41]
	v_add_u32_e32 v230, s51, v230
	s_add_i32 m0, s46, 0xa000
	v_mfma_f32_16x16x32_bf16 v[74:77], v[144:147], v[212:215], v[74:77]
	global_load_lds_dwordx4 v230, s[40:41]
	v_add_u32_e32 v230, s51, v230
	s_add_i32 m0, s46, 0xb000
	v_mfma_f32_16x16x32_bf16 v[78:81], v[148:151], v[212:215], v[78:81]
	global_load_lds_dwordx4 v230, s[40:41]
	v_add_u32_e32 v230, s51, v230
	s_add_i32 m0, s46, 0xc000
	v_mfma_f32_16x16x32_bf16 v[82:85], v[136:139], v[216:219], v[82:85]
	global_load_lds_dwordx4 v230, s[40:41]
	v_add_u32_e32 v230, s51, v230
	s_add_i32 m0, s46, 0xd000
	v_mfma_f32_16x16x32_bf16 v[86:89], v[140:143], v[216:219], v[86:89]
	global_load_lds_dwordx4 v230, s[40:41]
	v_add_u32_e32 v230, s51, v230
	s_add_i32 m0, s46, 0xe000
	v_mfma_f32_16x16x32_bf16 v[92:95], v[144:147], v[216:219], v[92:95]
	global_load_lds_dwordx4 v230, s[40:41]
	v_add_u32_e32 v230, s51, v230
	s_add_i32 m0, s46, 0xf000
	v_mfma_f32_16x16x32_bf16 v[96:99], v[148:151], v[216:219], v[96:99]
	global_load_lds_dwordx4 v230, s[40:41]
	s_add_i32 m0, s46, 0x10000
	v_mfma_f32_16x16x32_bf16 v[100:103], v[136:139], v[220:223], v[100:103]
	global_load_lds_dwordx4 v228, s[42:43]
	v_add_u32_e32 v230, s51, v228
	s_add_i32 m0, s46, 0x11000
	v_mfma_f32_16x16x32_bf16 v[104:107], v[140:143], v[220:223], v[104:107]
	global_load_lds_dwordx4 v230, s[42:43]
	v_add_u32_e32 v230, s51, v230
	s_add_i32 m0, s46, 0x12000
	v_mfma_f32_16x16x32_bf16 v[108:111], v[144:147], v[220:223], v[108:111]
	global_load_lds_dwordx4 v230, s[42:43]
	v_add_u32_e32 v230, s51, v230
	s_add_i32 m0, s46, 0x13000
	v_mfma_f32_16x16x32_bf16 v[112:115], v[148:151], v[220:223], v[112:115]
	global_load_lds_dwordx4 v230, s[42:43]
	v_mfma_f32_16x16x32_bf16 v[116:119], v[136:139], v[224:227], v[116:119]
	v_mfma_f32_16x16x32_bf16 v[120:123], v[140:143], v[224:227], v[120:123]
	v_mfma_f32_16x16x32_bf16 v[124:127], v[144:147], v[224:227], v[124:127]
	v_mfma_f32_16x16x32_bf16 v[128:131], v[148:151], v[224:227], v[128:131]
	ds_read_b128 v[212:215], v235 offset:8192
	ds_read_b128 v[216:219], v235 offset:10240
	ds_read_b128 v[220:223], v235 offset:12288
	ds_read_b128 v[224:227], v235 offset:14336
	s_waitcnt lgkmcnt(4)
	v_mfma_f32_16x16x32_bf16 v[2:5], v[152:155], v[196:199], v[2:5]
	v_mfma_f32_16x16x32_bf16 v[6:9], v[156:159], v[196:199], v[6:9]
	v_mfma_f32_16x16x32_bf16 v[10:13], v[160:163], v[196:199], v[10:13]
	v_mfma_f32_16x16x32_bf16 v[14:17], v[164:167], v[196:199], v[14:17]
	v_mfma_f32_16x16x32_bf16 v[18:21], v[152:155], v[200:203], v[18:21]
	v_mfma_f32_16x16x32_bf16 v[22:25], v[156:159], v[200:203], v[22:25]
	v_mfma_f32_16x16x32_bf16 v[26:29], v[160:163], v[200:203], v[26:29]
	v_mfma_f32_16x16x32_bf16 v[30:33], v[164:167], v[200:203], v[30:33]
	v_mfma_f32_16x16x32_bf16 v[34:37], v[152:155], v[204:207], v[34:37]
	v_mfma_f32_16x16x32_bf16 v[38:41], v[156:159], v[204:207], v[38:41]
	v_mfma_f32_16x16x32_bf16 v[42:45], v[160:163], v[204:207], v[42:45]
	v_mfma_f32_16x16x32_bf16 v[46:49], v[164:167], v[204:207], v[46:49]
	v_mfma_f32_16x16x32_bf16 v[50:53], v[152:155], v[208:211], v[50:53]
	v_mfma_f32_16x16x32_bf16 v[54:57], v[156:159], v[208:211], v[54:57]
	v_mfma_f32_16x16x32_bf16 v[58:61], v[160:163], v[208:211], v[58:61]
	v_mfma_f32_16x16x32_bf16 v[62:65], v[164:167], v[208:211], v[62:65]
	s_waitcnt lgkmcnt(0)
	v_mfma_f32_16x16x32_bf16 v[66:69], v[152:155], v[212:215], v[66:69]
	v_mfma_f32_16x16x32_bf16 v[70:73], v[156:159], v[212:215], v[70:73]
	v_mfma_f32_16x16x32_bf16 v[74:77], v[160:163], v[212:215], v[74:77]
	v_mfma_f32_16x16x32_bf16 v[78:81], v[164:167], v[212:215], v[78:81]
	v_mfma_f32_16x16x32_bf16 v[82:85], v[152:155], v[216:219], v[82:85]
	v_mfma_f32_16x16x32_bf16 v[86:89], v[156:159], v[216:219], v[86:89]
	v_mfma_f32_16x16x32_bf16 v[92:95], v[160:163], v[216:219], v[92:95]
	v_mfma_f32_16x16x32_bf16 v[96:99], v[164:167], v[216:219], v[96:99]
	v_mfma_f32_16x16x32_bf16 v[100:103], v[152:155], v[220:223], v[100:103]
	v_mfma_f32_16x16x32_bf16 v[104:107], v[156:159], v[220:223], v[104:107]
	v_mfma_f32_16x16x32_bf16 v[108:111], v[160:163], v[220:223], v[108:111]
	v_mfma_f32_16x16x32_bf16 v[112:115], v[164:167], v[220:223], v[112:115]
	v_mfma_f32_16x16x32_bf16 v[116:119], v[152:155], v[224:227], v[116:119]
	v_mfma_f32_16x16x32_bf16 v[120:123], v[156:159], v[224:227], v[120:123]
	v_mfma_f32_16x16x32_bf16 v[124:127], v[160:163], v[224:227], v[124:127]
	v_mfma_f32_16x16x32_bf16 v[128:131], v[164:167], v[224:227], v[128:131]
	s_setprio 0
	s_waitcnt vmcnt(0)
	s_barrier
;     ...
;     for (int m = 0; m < 4; ++m) af0[m] = *(const bf16x8*)(smem + cur + (abase + m * 2048));
; #pragma unroll
;     for (int n = 0; n < NT; ++n) bf0[n] = *(const bf16x8*)(smem + cur + (bbase + n * 2048));
; #pragma unroll
;     for (int m = 0; m < 4; ++m) af1[m] = *(const bf16x8*)(smem + cur + ((abase + m * 2048) ^ 64));
; #pragma unroll
;     for (int n = 0; n < NT; ++n) bf1[n] = *(const bf16x8*)(smem + cur + ((bbase + n * 2048) ^ 64));
;     __builtin_amdgcn_sched_barrier(0);
;     __builtin_amdgcn_s_setprio(1);
; #pragma unroll
;     for (int m = 0; m < 4; ++m)
; #pragma unroll
;       for (int n = 0; n < NT; ++n) acc[m][n] = __builtin_amdgcn_mfma_f32_16x16x32_bf16(bf0[n], af0[m], acc[m][n], 0, 0, 0);
; #pragma unroll
;     for (int m = 0; m < 4; ++m)
; #pragma unroll
;       for (int n = 0; n < NT; ++n) acc[m][n] = __builtin_amdgcn_mfma_f32_16x16x32_bf16(bf1[n], af1[m], acc[m][n], 0, 0, 0);
;     __builtin_amdgcn_s_setprio(0);
;     }
;     __builtin_amdgcn_sched_barrier(0);
;     asm volatile("s_waitcnt vmcnt(0)" ::: "memory");
;     __syncthreads();
;   __device__ __forceinline__ void next(char* smem) {
;     if (!cnt) { e += nb; return; }
;     if (threadIdx.x == 0) *(volatile int*)smem = (int)tick + nb;
	ds_read_b128 v[136:139], v232
	ds_read_b128 v[140:143], v232 offset:2048
	ds_read_b128 v[144:147], v232 offset:4096
	ds_read_b128 v[148:151], v232 offset:6144
	ds_read_b128 v[196:199], v231 offset:32768
	ds_read_b128 v[200:203], v231 offset:34816
	ds_read_b128 v[204:207], v231 offset:36864
	ds_read_b128 v[208:211], v231 offset:38912
	ds_read_b128 v[152:155], v236
	ds_read_b128 v[156:159], v236 offset:2048
	ds_read_b128 v[160:163], v236 offset:4096
	ds_read_b128 v[164:167], v236 offset:6144
	ds_read_b128 v[212:215], v231 offset:40960
	ds_read_b128 v[216:219], v231 offset:43008
	ds_read_b128 v[220:223], v231 offset:45056
	ds_read_b128 v[224:227], v231 offset:47104
	s_setprio 1
	s_waitcnt lgkmcnt(8)
	v_mfma_f32_16x16x32_bf16 v[2:5], v[136:139], v[196:199], v[2:5]
	v_mfma_f32_16x16x32_bf16 v[6:9], v[140:143], v[196:199], v[6:9]
	v_mfma_f32_16x16x32_bf16 v[10:13], v[144:147], v[196:199], v[10:13]
	v_mfma_f32_16x16x32_bf16 v[14:17], v[148:151], v[196:199], v[14:17]
	v_mfma_f32_16x16x32_bf16 v[18:21], v[136:139], v[200:203], v[18:21]
	v_mfma_f32_16x16x32_bf16 v[22:25], v[140:143], v[200:203], v[22:25]
	v_mfma_f32_16x16x32_bf16 v[26:29], v[144:147], v[200:203], v[26:29]
	v_mfma_f32_16x16x32_bf16 v[30:33], v[148:151], v[200:203], v[30:33]
	v_mfma_f32_16x16x32_bf16 v[34:37], v[136:139], v[204:207], v[34:37]
	v_mfma_f32_16x16x32_bf16 v[38:41], v[140:143], v[204:207], v[38:41]
	v_mfma_f32_16x16x32_bf16 v[42:45], v[144:147], v[204:207], v[42:45]
	v_mfma_f32_16x16x32_bf16 v[46:49], v[148:151], v[204:207], v[46:49]
	v_mfma_f32_16x16x32_bf16 v[50:53], v[136:139], v[208:211], v[50:53]
	v_mfma_f32_16x16x32_bf16 v[54:57], v[140:143], v[208:211], v[54:57]
	v_mfma_f32_16x16x32_bf16 v[58:61], v[144:147], v[208:211], v[58:61]
	v_mfma_f32_16x16x32_bf16 v[62:65], v[148:151], v[208:211], v[62:65]
	s_waitcnt lgkmcnt(0)
	ds_read_b128 v[196:199], v235 offset:32768
	ds_read_b128 v[200:203], v235 offset:34816
	ds_read_b128 v[204:207], v235 offset:36864
	ds_read_b128 v[208:211], v235 offset:38912
	v_mfma_f32_16x16x32_bf16 v[66:69], v[136:139], v[212:215], v[66:69]
	v_mfma_f32_16x16x32_bf16 v[70:73], v[140:143], v[212:215], v[70:73]
	v_mfma_f32_16x16x32_bf16 v[74:77], v[144:147], v[212:215], v[74:77]
	v_mfma_f32_16x16x32_bf16 v[78:81], v[148:151], v[212:215], v[78:81]
	v_mfma_f32_16x16x32_bf16 v[82:85], v[136:139], v[216:219], v[82:85]
	v_mfma_f32_16x16x32_bf16 v[86:89], v[140:143], v[216:219], v[86:89]
	v_mfma_f32_16x16x32_bf16 v[92:95], v[144:147], v[216:219], v[92:95]
	v_mfma_f32_16x16x32_bf16 v[96:99], v[148:151], v[216:219], v[96:99]
	v_mfma_f32_16x16x32_bf16 v[100:103], v[136:139], v[220:223], v[100:103]
	v_mfma_f32_16x16x32_bf16 v[104:107], v[140:143], v[220:223], v[104:107]
	v_mfma_f32_16x16x32_bf16 v[108:111], v[144:147], v[220:223], v[108:111]
	v_mfma_f32_16x16x32_bf16 v[112:115], v[148:151], v[220:223], v[112:115]
	v_mfma_f32_16x16x32_bf16 v[116:119], v[136:139], v[224:227], v[116:119]
	v_mfma_f32_16x16x32_bf16 v[120:123], v[140:143], v[224:227], v[120:123]
	v_mfma_f32_16x16x32_bf16 v[124:127], v[144:147], v[224:227], v[124:127]
	v_mfma_f32_16x16x32_bf16 v[128:131], v[148:151], v[224:227], v[128:131]
	ds_read_b128 v[212:215], v235 offset:40960
	ds_read_b128 v[216:219], v235 offset:43008
	ds_read_b128 v[220:223], v235 offset:45056
	ds_read_b128 v[224:227], v235 offset:47104
	s_waitcnt lgkmcnt(4)
	v_mfma_f32_16x16x32_bf16 v[2:5], v[152:155], v[196:199], v[2:5]
	v_mfma_f32_16x16x32_bf16 v[6:9], v[156:159], v[196:199], v[6:9]
	v_mfma_f32_16x16x32_bf16 v[10:13], v[160:163], v[196:199], v[10:13]
	v_mfma_f32_16x16x32_bf16 v[14:17], v[164:167], v[196:199], v[14:17]
	v_mfma_f32_16x16x32_bf16 v[18:21], v[152:155], v[200:203], v[18:21]
	v_mfma_f32_16x16x32_bf16 v[22:25], v[156:159], v[200:203], v[22:25]
	v_mfma_f32_16x16x32_bf16 v[26:29], v[160:163], v[200:203], v[26:29]
	v_mfma_f32_16x16x32_bf16 v[30:33], v[164:167], v[200:203], v[30:33]
	v_mfma_f32_16x16x32_bf16 v[34:37], v[152:155], v[204:207], v[34:37]
	v_mfma_f32_16x16x32_bf16 v[38:41], v[156:159], v[204:207], v[38:41]
	v_mfma_f32_16x16x32_bf16 v[42:45], v[160:163], v[204:207], v[42:45]
	v_mfma_f32_16x16x32_bf16 v[46:49], v[164:167], v[204:207], v[46:49]
	v_mfma_f32_16x16x32_bf16 v[50:53], v[152:155], v[208:211], v[50:53]
	v_mfma_f32_16x16x32_bf16 v[54:57], v[156:159], v[208:211], v[54:57]
	v_mfma_f32_16x16x32_bf16 v[58:61], v[160:163], v[208:211], v[58:61]
	v_mfma_f32_16x16x32_bf16 v[62:65], v[164:167], v[208:211], v[62:65]
	s_waitcnt lgkmcnt(0)
	v_mfma_f32_16x16x32_bf16 v[66:69], v[152:155], v[212:215], v[66:69]
	v_mfma_f32_16x16x32_bf16 v[70:73], v[156:159], v[212:215], v[70:73]
	v_mfma_f32_16x16x32_bf16 v[74:77], v[160:163], v[212:215], v[74:77]
	v_mfma_f32_16x16x32_bf16 v[78:81], v[164:167], v[212:215], v[78:81]
	v_mfma_f32_16x16x32_bf16 v[82:85], v[152:155], v[216:219], v[82:85]
	v_mfma_f32_16x16x32_bf16 v[86:89], v[156:159], v[216:219], v[86:89]
	v_mfma_f32_16x16x32_bf16 v[92:95], v[160:163], v[216:219], v[92:95]
	v_mfma_f32_16x16x32_bf16 v[96:99], v[164:167], v[216:219], v[96:99]
	v_mfma_f32_16x16x32_bf16 v[100:103], v[152:155], v[220:223], v[100:103]
	v_mfma_f32_16x16x32_bf16 v[104:107], v[156:159], v[220:223], v[104:107]
	v_mfma_f32_16x16x32_bf16 v[108:111], v[160:163], v[220:223], v[108:111]
	v_mfma_f32_16x16x32_bf16 v[112:115], v[164:167], v[220:223], v[112:115]
	v_mfma_f32_16x16x32_bf16 v[116:119], v[152:155], v[224:227], v[116:119]
	v_mfma_f32_16x16x32_bf16 v[120:123], v[156:159], v[224:227], v[120:123]
	v_mfma_f32_16x16x32_bf16 v[124:127], v[160:163], v[224:227], v[124:127]
	v_mfma_f32_16x16x32_bf16 v[128:131], v[164:167], v[224:227], v[128:131]
	s_setprio 0
	s_waitcnt vmcnt(0)
	s_barrier
	s_and_saveexec_b64 s[48:49], s[62:63]
	s_cbranch_execz .Lrs_tk1
	v_add_u32_e32 v0, s73, v233
	ds_write_b32 v1, v0
;   __device__ __forceinline__ void next(char* smem) {
;     if (!cnt) { e += nb; return; }
;     if (threadIdx.x == 0) *(volatile int*)smem = (int)tick + nb;
;     __syncthreads();
;     e = *(volatile int*)smem;
;     __syncthreads();
;   }
; __device__ __forceinline__ void phase_resid_gemm(const Params& p, const bf16_t* A, int lda, const bf16_t* Wt, int K, int l, int gate_k, float scale,
;                                  bool from_input, int mrows, char* smem, unsigned* tk) {
;     ...
;     const int bi = mod_idx(tm * 128);
;     const float* gate = mods_ptr(p, l, bi, gate_k);
;     const int row0 = tm * 128 + wr * 64 + fr, col0 = tn * 128 + wc * 64 + fq * 4;
;     const float* xi = xrow_ptr(p, from_input, row0) + col0;
;     float* xo = xrow_out(p, row0) + col0;
;     float4 gv[4];
; #pragma unroll
;     for (int n = 0; n < 4; ++n) {
;       gv[n] = *(const float4*)(gate + col0 + n * 16);
;       gv[n].x *= scale; gv[n].y *= scale; gv[n].z *= scale; gv[n].w *= scale;
;     }
; #pragma unroll
;     for (int m = 0; m < 4; ++m) {
; #pragma unroll
;       for (int n = 0; n < 4; ++n) {
;         const float4 xv = *(const float4*)(xi + (m * 16) * DM + n * 16);
;         float4 ov;
;         ov.x = xv.x + gv[n].x * acc[m][n][0];
;         ov.y = xv.y + gv[n].y * acc[m][n][1];
;         ov.z = xv.z + gv[n].z * acc[m][n][2];
;         ov.w = xv.w + gv[n].w * acc[m][n][3];
;         *(float4*)(xo + (m * 16) * DM + n * 16) = ov;
.Lrs_tk1:
	s_or_b64 exec, exec, s[48:49]
	s_waitcnt lgkmcnt(0)
	s_barrier
	ds_read_b32 v0, v1
	s_waitcnt lgkmcnt(0)
	v_readfirstlane_b32 s44, v0
	s_barrier
	s_lshr_b32 s68, s47, 3
	s_sub_i32 s45, s47, 128
	s_add_u32 s66, s100, 0x3380000
	s_addc_u32 s67, s101, 0
	s_cmp_lt_u32 s47, 128
	s_cselect_b32 s45, s47, s45
	s_cselect_b32 s34, s96, s66
	s_cselect_b32 s35, s97, s67
	s_cselect_b32 s66, s60, s64
	s_cselect_b32 s67, s61, s65
	s_cselect_b32 s68, s68, 16
	s_lshl_b32 s45, s45, 20
	s_lshl_b32 s49, s98, 9
	s_add_u32 s45, s45, s49
	s_add_u32 s34, s34, s45
	s_addc_u32 s35, s35, 0
	s_add_u32 s66, s66, s45
	s_addc_u32 s67, s67, 0
	s_cmp_eq_u32 s57, 1
	s_cselect_b32 s66, s66, s34
	s_cselect_b32 s67, s67, s35
	s_add_i32 s68, s68, s56
	s_mul_i32 s68, s68, 9
	s_add_i32 s68, s68, s55
	s_lshl_b32 s68, s68, 12
	s_add_u32 s68, s68, s49
	s_add_u32 s48, s100, 0x1e2a0000
	s_addc_u32 s49, s101, 0
	s_add_u32 s48, s48, s68
	s_addc_u32 s49, s49, 0
	global_load_dwordx4 v[136:139], v237, s[48:49]
	global_load_dwordx4 v[140:143], v237, s[48:49] offset:64
	global_load_dwordx4 v[144:147], v237, s[48:49] offset:128
	global_load_dwordx4 v[148:151], v237, s[48:49] offset:192
	global_load_dwordx4 v[196:199], v234, s[66:67]
	global_load_dwordx4 v[200:203], v234, s[66:67] offset:64
	global_load_dwordx4 v[204:207], v234, s[66:67] offset:128
	global_load_dwordx4 v[208:211], v234, s[66:67] offset:192
	s_add_u32 s66, s66, 0x10000
	s_addc_u32 s67, s67, 0
	global_load_dwordx4 v[212:215], v234, s[66:67]
	global_load_dwordx4 v[216:219], v234, s[66:67] offset:64
	global_load_dwordx4 v[220:223], v234, s[66:67] offset:128
	global_load_dwordx4 v[224:227], v234, s[66:67] offset:192
	s_add_u32 s66, s66, 0x10000
	s_addc_u32 s67, s67, 0
	s_waitcnt vmcnt(4)
	v_mul_f32_e32 v136, v246, v136
	v_mul_f32_e32 v137, v246, v137
	v_mul_f32_e32 v138, v246, v138
	v_mul_f32_e32 v139, v246, v139
	v_mul_f32_e32 v140, v246, v140
	v_mul_f32_e32 v141, v246, v141
	v_mul_f32_e32 v142, v246, v142
	v_mul_f32_e32 v143, v246, v143
	v_mul_f32_e32 v144, v246, v144
	v_mul_f32_e32 v145, v246, v145
	v_mul_f32_e32 v146, v246, v146
	v_mul_f32_e32 v147, v246, v147
	v_mul_f32_e32 v148, v246, v148
	v_mul_f32_e32 v149, v246, v149
	v_mul_f32_e32 v150, v246, v150
	v_mul_f32_e32 v151, v246, v151
	v_fma_f32 v2, v2, v136, v196
	v_fma_f32 v3, v3, v137, v197
	v_fma_f32 v4, v4, v138, v198
	v_fma_f32 v5, v5, v139, v199
	v_fma_f32 v6, v6, v140, v200
	v_fma_f32 v7, v7, v141, v201
	v_fma_f32 v8, v8, v142, v202
	v_fma_f32 v9, v9, v143, v203
	v_fma_f32 v10, v10, v144, v204
	v_fma_f32 v11, v11, v145, v205
	v_fma_f32 v12, v12, v146, v206
	v_fma_f32 v13, v13, v147, v207
	v_fma_f32 v14, v14, v148, v208
	v_fma_f32 v15, v15, v149, v209
	v_fma_f32 v16, v16, v150, v210
	v_fma_f32 v17, v17, v151, v211
	global_store_dwordx4 v234, v[2:5], s[34:35]
	global_store_dwordx4 v234, v[6:9], s[34:35] offset:64
	global_store_dwordx4 v234, v[10:13], s[34:35] offset:128
	global_store_dwordx4 v234, v[14:17], s[34:35] offset:192
	s_add_u32 s34, s34, 0x10000
	s_addc_u32 s35, s35, 0
	global_load_dwordx4 v[196:199], v234, s[66:67]
	global_load_dwordx4 v[200:203], v234, s[66:67] offset:64
	global_load_dwordx4 v[204:207], v234, s[66:67] offset:128
	global_load_dwordx4 v[208:211], v234, s[66:67] offset:192
	s_add_u32 s66, s66, 0x10000
	s_addc_u32 s67, s67, 0
	s_waitcnt vmcnt(8)
	v_fma_f32 v18, v18, v136, v212
	v_fma_f32 v19, v19, v137, v213
	v_fma_f32 v20, v20, v138, v214
	v_fma_f32 v21, v21, v139, v215
	v_fma_f32 v22, v22, v140, v216
	v_fma_f32 v23, v23, v141, v217
	v_fma_f32 v24, v24, v142, v218
	v_fma_f32 v25, v25, v143, v219
	v_fma_f32 v26, v26, v144, v220
	v_fma_f32 v27, v27, v145, v221
	v_fma_f32 v28, v28, v146, v222
	v_fma_f32 v29, v29, v147, v223
	v_fma_f32 v30, v30, v148, v224
	v_fma_f32 v31, v31, v149, v225
	v_fma_f32 v32, v32, v150, v226
	v_fma_f32 v33, v33, v151, v227
	global_store_dwordx4 v234, v[18:21], s[34:35]
	global_store_dwordx4 v234, v[22:25], s[34:35] offset:64
	global_store_dwordx4 v234, v[26:29], s[34:35] offset:128
	global_store_dwordx4 v234, v[30:33], s[34:35] offset:192
	s_add_u32 s34, s34, 0x10000
	s_addc_u32 s35, s35, 0
	global_load_dwordx4 v[212:215], v234, s[66:67]
	global_load_dwordx4 v[216:219], v234, s[66:67] offset:64
	global_load_dwordx4 v[220:223], v234, s[66:67] offset:128
	global_load_dwordx4 v[224:227], v234, s[66:67] offset:192
	s_add_u32 s66, s66, 0x10000
	s_addc_u32 s67, s67, 0
	s_waitcnt vmcnt(8)
	v_fma_f32 v34, v34, v136, v196
	v_fma_f32 v35, v35, v137, v197
	v_fma_f32 v36, v36, v138, v198
	v_fma_f32 v37, v37, v139, v199
	v_fma_f32 v38, v38, v140, v200
	v_fma_f32 v39, v39, v141, v201
	v_fma_f32 v40, v40, v142, v202
	v_fma_f32 v41, v41, v143, v203
	v_fma_f32 v42, v42, v144, v204
	v_fma_f32 v43, v43, v145, v205
	v_fma_f32 v44, v44, v146, v206
	v_fma_f32 v45, v45, v147, v207
	v_fma_f32 v46, v46, v148, v208
	v_fma_f32 v47, v47, v149, v209
	v_fma_f32 v48, v48, v150, v210
	v_fma_f32 v49, v49, v151, v211
	global_store_dwordx4 v234, v[34:37], s[34:35]
	global_store_dwordx4 v234, v[38:41], s[34:35] offset:64
	global_store_dwordx4 v234, v[42:45], s[34:35] offset:128
	global_store_dwordx4 v234, v[46:49], s[34:35] offset:192
	s_add_u32 s34, s34, 0x10000
	s_addc_u32 s35, s35, 0
	global_load_dwordx4 v[196:199], v234, s[66:67]
	global_load_dwordx4 v[200:203], v234, s[66:67] offset:64
	global_load_dwordx4 v[204:207], v234, s[66:67] offset:128
	global_load_dwordx4 v[208:211], v234, s[66:67] offset:192
	s_add_u32 s66, s66, 0x10000
	s_addc_u32 s67, s67, 0
	s_waitcnt vmcnt(8)
; __device__ __forceinline__ void phase_resid_gemm(const Params& p, const bf16_t* A, int lda, const bf16_t* Wt, int K, int l, int gate_k, float scale,
;                                  bool from_input, int mrows, char* smem, unsigned* tk) {
;     ...
; #pragma unroll
;     for (int m = 0; m < 4; ++m) {
; #pragma unroll
;       for (int n = 0; n < 4; ++n) {
;         const float4 xv = *(const float4*)(xi + (m * 16) * DM + n * 16);
;         float4 ov;
;         ov.x = xv.x + gv[n].x * acc[m][n][0];
;         ov.y = xv.y + gv[n].y * acc[m][n][1];
;         ov.z = xv.z + gv[n].z * acc[m][n][2];
;         ov.w = xv.w + gv[n].w * acc[m][n][3];
;         *(float4*)(xo + (m * 16) * DM + n * 16) = ov;
;       }
;       __builtin_amdgcn_sched_barrier(0);
;     }
	v_fma_f32 v50, v50, v136, v212
	v_fma_f32 v51, v51, v137, v213
	v_fma_f32 v52, v52, v138, v214
	v_fma_f32 v53, v53, v139, v215
	v_fma_f32 v54, v54, v140, v216
	v_fma_f32 v55, v55, v141, v217
	v_fma_f32 v56, v56, v142, v218
	v_fma_f32 v57, v57, v143, v219
	v_fma_f32 v58, v58, v144, v220
	v_fma_f32 v59, v59, v145, v221
	v_fma_f32 v60, v60, v146, v222
	v_fma_f32 v61, v61, v147, v223
	v_fma_f32 v62, v62, v148, v224
	v_fma_f32 v63, v63, v149, v225
	v_fma_f32 v64, v64, v150, v226
	v_fma_f32 v65, v65, v151, v227
	global_store_dwordx4 v234, v[50:53], s[34:35]
	global_store_dwordx4 v234, v[54:57], s[34:35] offset:64
	global_store_dwordx4 v234, v[58:61], s[34:35] offset:128
	global_store_dwordx4 v234, v[62:65], s[34:35] offset:192
	s_add_u32 s34, s34, 0x10000
	s_addc_u32 s35, s35, 0
	global_load_dwordx4 v[212:215], v234, s[66:67]
	global_load_dwordx4 v[216:219], v234, s[66:67] offset:64
	global_load_dwordx4 v[220:223], v234, s[66:67] offset:128
	global_load_dwordx4 v[224:227], v234, s[66:67] offset:192
	s_add_u32 s66, s66, 0x10000
	s_addc_u32 s67, s67, 0
	s_waitcnt vmcnt(8)
	v_fma_f32 v66, v66, v136, v196
	v_fma_f32 v67, v67, v137, v197
	v_fma_f32 v68, v68, v138, v198
	v_fma_f32 v69, v69, v139, v199
	v_fma_f32 v70, v70, v140, v200
	v_fma_f32 v71, v71, v141, v201
	v_fma_f32 v72, v72, v142, v202
	v_fma_f32 v73, v73, v143, v203
	v_fma_f32 v74, v74, v144, v204
	v_fma_f32 v75, v75, v145, v205
	v_fma_f32 v76, v76, v146, v206
	v_fma_f32 v77, v77, v147, v207
	v_fma_f32 v78, v78, v148, v208
	v_fma_f32 v79, v79, v149, v209
	v_fma_f32 v80, v80, v150, v210
	v_fma_f32 v81, v81, v151, v211
	global_store_dwordx4 v234, v[66:69], s[34:35]
	global_store_dwordx4 v234, v[70:73], s[34:35] offset:64
	global_store_dwordx4 v234, v[74:77], s[34:35] offset:128
	global_store_dwordx4 v234, v[78:81], s[34:35] offset:192
	s_add_u32 s34, s34, 0x10000
	s_addc_u32 s35, s35, 0
	global_load_dwordx4 v[196:199], v234, s[66:67]
	global_load_dwordx4 v[200:203], v234, s[66:67] offset:64
	global_load_dwordx4 v[204:207], v234, s[66:67] offset:128
	global_load_dwordx4 v[208:211], v234, s[66:67] offset:192
	s_add_u32 s66, s66, 0x10000
	s_addc_u32 s67, s67, 0
	s_waitcnt vmcnt(8)
	v_fma_f32 v82, v82, v136, v212
	v_fma_f32 v83, v83, v137, v213
	v_fma_f32 v84, v84, v138, v214
	v_fma_f32 v85, v85, v139, v215
	v_fma_f32 v86, v86, v140, v216
	v_fma_f32 v87, v87, v141, v217
	v_fma_f32 v88, v88, v142, v218
	v_fma_f32 v89, v89, v143, v219
	v_fma_f32 v92, v92, v144, v220
	v_fma_f32 v93, v93, v145, v221
	v_fma_f32 v94, v94, v146, v222
	v_fma_f32 v95, v95, v147, v223
	v_fma_f32 v96, v96, v148, v224
	v_fma_f32 v97, v97, v149, v225
	v_fma_f32 v98, v98, v150, v226
	v_fma_f32 v99, v99, v151, v227
	global_store_dwordx4 v234, v[82:85], s[34:35]
	global_store_dwordx4 v234, v[86:89], s[34:35] offset:64
	global_store_dwordx4 v234, v[92:95], s[34:35] offset:128
	global_store_dwordx4 v234, v[96:99], s[34:35] offset:192
	s_add_u32 s34, s34, 0x10000
	s_addc_u32 s35, s35, 0
	global_load_dwordx4 v[212:215], v234, s[66:67]
	global_load_dwordx4 v[216:219], v234, s[66:67] offset:64
	global_load_dwordx4 v[220:223], v234, s[66:67] offset:128
	global_load_dwordx4 v[224:227], v234, s[66:67] offset:192
	s_add_u32 s66, s66, 0x10000
	s_addc_u32 s67, s67, 0
	s_waitcnt vmcnt(8)
	v_fma_f32 v100, v100, v136, v196
	v_fma_f32 v101, v101, v137, v197
	v_fma_f32 v102, v102, v138, v198
	v_fma_f32 v103, v103, v139, v199
	v_fma_f32 v104, v104, v140, v200
	v_fma_f32 v105, v105, v141, v201
	v_fma_f32 v106, v106, v142, v202
	v_fma_f32 v107, v107, v143, v203
	v_fma_f32 v108, v108, v144, v204
	v_fma_f32 v109, v109, v145, v205
	v_fma_f32 v110, v110, v146, v206
	v_fma_f32 v111, v111, v147, v207
	v_fma_f32 v112, v112, v148, v208
	v_fma_f32 v113, v113, v149, v209
	v_fma_f32 v114, v114, v150, v210
	v_fma_f32 v115, v115, v151, v211
	global_store_dwordx4 v234, v[100:103], s[34:35]
	global_store_dwordx4 v234, v[104:107], s[34:35] offset:64
	global_store_dwordx4 v234, v[108:111], s[34:35] offset:128
	global_store_dwordx4 v234, v[112:115], s[34:35] offset:192
	s_add_u32 s34, s34, 0x10000
	s_addc_u32 s35, s35, 0
	s_waitcnt vmcnt(4)
	v_fma_f32 v116, v116, v136, v212
	v_fma_f32 v117, v117, v137, v213
	v_fma_f32 v118, v118, v138, v214
	v_fma_f32 v119, v119, v139, v215
	v_fma_f32 v120, v120, v140, v216
	v_fma_f32 v121, v121, v141, v217
	v_fma_f32 v122, v122, v142, v218
	v_fma_f32 v123, v123, v143, v219
	v_fma_f32 v124, v124, v144, v220
	v_fma_f32 v125, v125, v145, v221
	v_fma_f32 v126, v126, v146, v222
	v_fma_f32 v127, v127, v147, v223
	v_fma_f32 v128, v128, v148, v224
	v_fma_f32 v129, v129, v149, v225
	v_fma_f32 v130, v130, v150, v226
	v_fma_f32 v131, v131, v151, v227
	global_store_dwordx4 v234, v[116:119], s[34:35]
	global_store_dwordx4 v234, v[120:123], s[34:35] offset:64
	global_store_dwordx4 v234, v[124:127], s[34:35] offset:128
	global_store_dwordx4 v234, v[128:131], s[34:35] offset:192
	s_add_u32 s34, s34, 0x10000
	s_addc_u32 s35, s35, 0
	s_branch .Lrs_tile
; __device__ __forceinline__ void phase_resid_gemm(const Params& p, const bf16_t* A, int lda, const bf16_t* Wt, int K, int l, int gate_k, float scale,
;                                  bool from_input, int mrows, char* smem, unsigned* tk) {
;     ...
;   for (TileIter ti(mrows / 128, 8, 4, 8, tk); ti.valid();) {
;     int tm, tn; ti.get(tm, tn);
;     ti.prefetch();
;     f32x4 acc[4][4];
;     zero_acc<4>(acc);
;     gemm_main<4>(A + (size_t)tm * 128 * lda, lda, Wt + (size_t)tn * 128 * K, K, K, acc, smem);
;     ti.next(smem);
;     const int bi = mod_idx(tm * 128);
;     const float* gate = mods_ptr(p, l, bi, gate_k);
;     const int row0 = tm * 128 + wr * 64 + fr, col0 = tn * 128 + wc * 64 + fq * 4;
;     const float* xi = xrow_ptr(p, from_input, row0) + col0;
;     float* xo = xrow_out(p, row0) + col0;
;     float4 gv[4];
; #pragma unroll
;     for (int n = 0; n < 4; ++n) {
;       gv[n] = *(const float4*)(gate + col0 + n * 16);
;       gv[n].x *= scale; gv[n].y *= scale; gv[n].z *= scale; gv[n].w *= scale;
;     }
; #pragma unroll
;     for (int m = 0; m < 4; ++m) {
; #pragma unroll
;       for (int n = 0; n < 4; ++n) {
;         const float4 xv = *(const float4*)(xi + (m * 16) * DM + n * 16);
;         float4 ov;
;         ov.x = xv.x + gv[n].x * acc[m][n][0];
;         ov.y = xv.y + gv[n].y * acc[m][n][1];
;         ov.z = xv.z + gv[n].z * acc[m][n][2];
;         ov.w = xv.w + gv[n].w * acc[m][n][3];
;         *(float4*)(xo + (m * 16) * DM + n * 16) = ov;
;       }
;       __builtin_amdgcn_sched_barrier(0);
;     }
;   }
; }
.Lrs_exit:
	s_waitcnt vmcnt(0) lgkmcnt(0)
	v_readlane_b32 s40, v249, 0
	v_readlane_b32 s41, v249, 1
	v_readlane_b32 s42, v249, 2
	v_readlane_b32 s43, v249, 3
	v_readlane_b32 s44, v249, 4
	v_readlane_b32 s45, v249, 5
	v_readlane_b32 s46, v249, 6
	v_readlane_b32 s47, v249, 7
	v_mov_b32_e32 v92, s40
	v_mov_b32_e32 v93, s41
	v_mov_b32_e32 v94, s42
	v_mov_b32_e32 v95, s43
	v_mov_b32_e32 v96, s44
	v_mov_b32_e32 v97, s45
	v_mov_b32_e32 v98, s46
	v_mov_b32_e32 v99, s47
	v_readlane_b32 s40, v249, 8
	v_readlane_b32 s41, v249, 9
	v_readlane_b32 s42, v249, 10
	v_readlane_b32 s43, v249, 11
	v_readlane_b32 s44, v249, 12
	v_readlane_b32 s45, v249, 13
	v_readlane_b32 s46, v249, 14
	v_readlane_b32 s47, v249, 15
	v_mov_b32_e32 v100, s40
	v_mov_b32_e32 v101, s41
	v_mov_b32_e32 v102, s42
	v_mov_b32_e32 v103, s43
	v_mov_b32_e32 v104, s44
	v_mov_b32_e32 v105, s45
	v_mov_b32_e32 v106, s46
	v_mov_b32_e32 v107, s47
	v_readlane_b32 s40, v249, 16
	v_readlane_b32 s41, v249, 17
	v_readlane_b32 s42, v249, 18
	v_readlane_b32 s43, v249, 19
	v_readlane_b32 s44, v249, 20
	v_readlane_b32 s45, v249, 21
	v_readlane_b32 s46, v249, 22
	v_readlane_b32 s47, v249, 23
	v_mov_b32_e32 v108, s40
	v_mov_b32_e32 v109, s41
	v_mov_b32_e32 v110, s42
	v_mov_b32_e32 v111, s43
	v_mov_b32_e32 v112, s44
	v_mov_b32_e32 v113, s45
	v_mov_b32_e32 v114, s46
	v_mov_b32_e32 v115, s47
	v_readlane_b32 s40, v249, 24
	v_readlane_b32 s41, v249, 25
	v_readlane_b32 s42, v249, 26
	v_readlane_b32 s43, v249, 27
	v_readlane_b32 s44, v249, 28
	v_readlane_b32 s45, v249, 29
	v_readlane_b32 s46, v249, 30
	v_readlane_b32 s47, v249, 31
	v_mov_b32_e32 v116, s40
	v_mov_b32_e32 v117, s41
	v_mov_b32_e32 v118, s42
	v_mov_b32_e32 v119, s43
	v_mov_b32_e32 v120, s44
	v_mov_b32_e32 v121, s45
	v_mov_b32_e32 v122, s46
	v_mov_b32_e32 v123, s47
	v_readlane_b32 s40, v249, 32
	v_readlane_b32 s41, v249, 33
	v_readlane_b32 s42, v249, 34
	v_readlane_b32 s43, v249, 35
	v_readlane_b32 s44, v249, 36
	v_readlane_b32 s45, v249, 37
	v_readlane_b32 s46, v249, 38
	v_readlane_b32 s47, v249, 39
	v_mov_b32_e32 v124, s40
	v_mov_b32_e32 v125, s41
	v_mov_b32_e32 v126, s42
	v_mov_b32_e32 v127, s43
	v_mov_b32_e32 v128, s44
	v_mov_b32_e32 v129, s45
	v_mov_b32_e32 v130, s46
	v_mov_b32_e32 v131, s47
	v_readlane_b32 s40, v249, 40
	v_readlane_b32 s41, v249, 41
	s_nop 1
	v_mov_b32_e32 v132, s40
	v_mov_b32_e32 v133, s41
	s_branch .LBB0_314
.LBB0_314:
	v_readlane_b32 s64, v250, 25
	v_readlane_b32 s65, v250, 26
